# lorak: LoRA GEMM runs 4 of 8 K-steps per tile from a per-column-group K origin (skipped steps multiply the zero padding of the fused LoRA weight)
# speedup vs baseline: 1.0042x; 1.0042x over previous
.LBB0_509:
	s_cmpk_gt_i32 s69, 0x2ff
	v_readfirstlane_b32 s40, v170
	s_waitcnt vmcnt(0) lgkmcnt(0)
	s_barrier
	s_cbranch_scc1 .LBB0_529
	s_add_u32 s41, s66, 0x8000000
	s_addc_u32 s42, s67, 0
	s_ashr_i32 s44, s69, 31
	s_lshr_b32 s0, s44, 29
	s_add_i32 s0, s69, s0
	s_lshr_b32 s12, s40, 6
	s_ashr_i32 s1, s0, 3
	s_and_b32 s0, s0, -8
	s_lshr_b32 s3, s40, 8
	s_lshl_b32 s43, s12, 10
	s_sub_i32 s0, s69, s0
	s_cmp_lt_i32 s0, 0
	s_movk_i32 s45, 0x61
	s_cselect_b32 s2, s45, 0x60
	s_mul_i32 s0, s2, s0
	s_add_i32 s0, s0, s1
	s_mul_hi_i32 s1, s0, 0x2aaaaaab
	s_lshr_b32 s2, s1, 31
	s_ashr_i32 s1, s1, 3
	s_add_i32 s1, s1, s2
	s_lshl_b32 s13, s1, 2
	s_mul_i32 s1, s1, 48
	s_sub_i32 s0, s0, s1
	s_bfe_i32 s1, s0, 0x80000
	s_bfe_u32 s1, s1, 0x2000d
	s_add_i32 s1, s0, s1
	s_bfe_i32 s2, s1, 0x80000
	s_and_b32 s1, s1, 0xfc
	s_sub_i32 s0, s0, s1
	s_sext_i32_i16 s2, s2
	s_sext_i32_i8 s0, s0
	s_lshr_b32 s2, s2, 2
	s_add_i32 s0, s13, s0
	s_ashr_i32 s1, s0, 31
	s_bfe_i64 s[16:17], s[2:3], 0x100000
	s_lshl_b64 s[14:15], s[0:1], 18
	s_lshl_b64 s[16:17], s[16:17], 18
	s_add_u32 s34, s41, s16
	s_addc_u32 s35, s42, s17
	s_bfe_u32 s98, s2, 0x20002
	s_add_i32 s99, s98, 1
	s_mul_i32 s98, s98, s99
	s_lshl_b32 s98, s98, 6
	s_add_u32 s34, s34, s98
	s_addc_u32 s35, s35, 0
	s_add_u32 s14, s14, s98
	s_addc_u32 s15, s15, 0
	s_add_i32 s46, s43, 0
	v_lshl_or_b32 v148, v148, 10, v145
	s_add_i32 m0, s46, 0x10000
	v_lshl_or_b32 v144, v144, 10, v145
	global_load_lds_dwordx4 v148, s[34:35]
	s_add_i32 m0, s46, 0x12000
	s_add_u32 s30, s38, s14
	v_lshl_or_b32 v150, v147, 10, v145
	global_load_lds_dwordx4 v144, s[34:35]
	s_addc_u32 s31, s39, s15
	s_mov_b32 m0, s46
	s_add_i32 s47, s46, 0x2000
	v_lshl_or_b32 v146, v146, 10, v145
	global_load_lds_dwordx4 v150, s[30:31]
	s_mov_b32 m0, s47
	s_add_u32 s14, s34, 0x20000
	global_load_lds_dwordx4 v146, s[30:31]
	s_addc_u32 s15, s35, 0
	s_add_i32 m0, s46, 0x14000
	v_mov_b32_e32 v153, 0
	global_load_lds_dwordx4 v148, s[14:15]
	s_add_i32 m0, s46, 0x16000
	v_mov_b32_e32 v149, v153
	global_load_lds_dwordx4 v144, s[14:15]
	s_add_u32 s14, s30, 0x20000
	s_addc_u32 s15, s31, 0
	s_add_i32 s48, s46, 0x4000
	s_mov_b32 m0, s48
	s_add_i32 s49, s46, 0x6000
	global_load_lds_dwordx4 v150, s[14:15]
	s_mov_b32 m0, s49
	v_mov_b32_e32 v145, v153
	global_load_lds_dwordx4 v146, s[14:15]
	v_mov_b32_e32 v151, v153
	v_mov_b32_e32 v147, v153
	s_mov_b32 s50, 0
	v_lshl_add_u64 v[6:7], s[34:35], 0, v[148:149]
	v_lshl_add_u64 v[4:5], s[34:35], 0, v[144:145]
	v_lshl_add_u64 v[2:3], s[30:31], 0, v[150:151]
	s_cmp_lg_u32 s3, 1
	v_lshl_add_u64 v[0:1], s[30:31], 0, v[146:147]
	s_cbranch_scc1 .LBB0_512
	s_barrier

.LBB0_516:
	s_ashr_i32 s25, s24, 31
	v_cmp_lt_i64_e32 vcc, s[26:27], v[158:159]
	s_lshl_b64 s[26:27], s[24:25], 18
	s_add_u32 s26, s38, s26
	s_addc_u32 s27, s39, s27
	s_lshr_b32 s98, s22, 2
	s_add_i32 s99, s98, 1
	s_mul_i32 s98, s98, s99
	s_lshl_b32 s98, s98, 6
	s_add_u32 s26, s26, s98
	s_addc_u32 s27, s27, 0
	s_and_b64 s[28:29], vcc, exec
	s_cselect_b32 s1, s27, s31
	s_cselect_b32 s25, s26, s30
	s_ashr_i32 s23, s22, 31
	s_lshl_b64 s[28:29], s[22:23], 18
	s_add_u32 s28, s41, s28
	s_addc_u32 s29, s42, s29
	s_add_u32 s28, s28, s98
	s_addc_u32 s29, s29, 0
	s_and_b64 s[36:37], vcc, exec
	s_cselect_b32 s23, s29, s35
	s_cselect_b32 s65, s28, s34
	s_add_u32 s30, s30, 0x20080
	s_addc_u32 s31, s31, 0
	s_add_u32 s66, s34, 0x100
	v_mov_b32_e32 v0, 0
	s_addc_u32 s67, s35, 0
	s_mov_b32 s80, -2
	v_mov_b32_e32 v1, v0
	v_mov_b32_e32 v2, v0
	v_mov_b32_e32 v3, v0
	v_mov_b32_e32 v4, v0
	v_mov_b32_e32 v5, v0
	v_mov_b32_e32 v6, v0
	v_mov_b32_e32 v7, v0
	v_mov_b32_e32 v16, v0
	v_mov_b32_e32 v17, v0
	v_mov_b32_e32 v18, v0
	v_mov_b32_e32 v19, v0
	v_mov_b32_e32 v20, v0
	v_mov_b32_e32 v21, v0
	v_mov_b32_e32 v22, v0
	v_mov_b32_e32 v23, v0
	v_mov_b32_e32 v32, v0
	v_mov_b32_e32 v33, v0
	v_mov_b32_e32 v34, v0
	v_mov_b32_e32 v35, v0
	v_mov_b32_e32 v36, v0
	v_mov_b32_e32 v37, v0
	v_mov_b32_e32 v38, v0
	v_mov_b32_e32 v39, v0
	v_mov_b32_e32 v48, v0
	v_mov_b32_e32 v49, v0
	v_mov_b32_e32 v50, v0
	v_mov_b32_e32 v51, v0
	v_mov_b32_e32 v52, v0
	v_mov_b32_e32 v53, v0
	v_mov_b32_e32 v54, v0
	v_mov_b32_e32 v55, v0
	v_mov_b32_e32 v8, v0
	v_mov_b32_e32 v9, v0
	v_mov_b32_e32 v10, v0
	v_mov_b32_e32 v11, v0
	v_mov_b32_e32 v12, v0
	v_mov_b32_e32 v13, v0
	v_mov_b32_e32 v14, v0
	v_mov_b32_e32 v15, v0
	v_mov_b32_e32 v24, v0
	v_mov_b32_e32 v25, v0
	v_mov_b32_e32 v26, v0
	v_mov_b32_e32 v27, v0
	v_mov_b32_e32 v28, v0
	v_mov_b32_e32 v29, v0
	v_mov_b32_e32 v30, v0
	v_mov_b32_e32 v31, v0
	v_mov_b32_e32 v40, v0
	v_mov_b32_e32 v41, v0
	v_mov_b32_e32 v42, v0
	v_mov_b32_e32 v43, v0
	v_mov_b32_e32 v44, v0
	v_mov_b32_e32 v45, v0
	v_mov_b32_e32 v46, v0
	v_mov_b32_e32 v47, v0
	v_mov_b32_e32 v56, v0
	v_mov_b32_e32 v57, v0
	v_mov_b32_e32 v58, v0
	v_mov_b32_e32 v59, v0
	v_mov_b32_e32 v60, v0
	v_mov_b32_e32 v61, v0
	v_mov_b32_e32 v62, v0
	v_mov_b32_e32 v63, v0
	v_mov_b32_e32 v72, v0
	v_mov_b32_e32 v73, v0
	v_mov_b32_e32 v74, v0
	v_mov_b32_e32 v75, v0
	v_mov_b32_e32 v76, v0
	v_mov_b32_e32 v77, v0
	v_mov_b32_e32 v78, v0
	v_mov_b32_e32 v79, v0
	v_mov_b32_e32 v96, v0
	v_mov_b32_e32 v97, v0
	v_mov_b32_e32 v98, v0
	v_mov_b32_e32 v99, v0
	v_mov_b32_e32 v100, v0
	v_mov_b32_e32 v101, v0
	v_mov_b32_e32 v102, v0
	v_mov_b32_e32 v103, v0
	v_mov_b32_e32 v112, v0
	v_mov_b32_e32 v113, v0
	v_mov_b32_e32 v114, v0
	v_mov_b32_e32 v115, v0
	v_mov_b32_e32 v116, v0
	v_mov_b32_e32 v117, v0
	v_mov_b32_e32 v118, v0
	v_mov_b32_e32 v119, v0
	v_mov_b32_e32 v128, v0
	v_mov_b32_e32 v129, v0
	v_mov_b32_e32 v130, v0
	v_mov_b32_e32 v131, v0
	v_mov_b32_e32 v132, v0
	v_mov_b32_e32 v133, v0
	v_mov_b32_e32 v134, v0
	v_mov_b32_e32 v135, v0
	v_mov_b32_e32 v88, v0
	v_mov_b32_e32 v89, v0
	v_mov_b32_e32 v90, v0
	v_mov_b32_e32 v91, v0
	v_mov_b32_e32 v92, v0
	v_mov_b32_e32 v93, v0
	v_mov_b32_e32 v94, v0
	v_mov_b32_e32 v95, v0
	v_mov_b32_e32 v104, v0
	v_mov_b32_e32 v105, v0
	v_mov_b32_e32 v106, v0
	v_mov_b32_e32 v107, v0
	v_mov_b32_e32 v108, v0
	v_mov_b32_e32 v109, v0
	v_mov_b32_e32 v110, v0
	v_mov_b32_e32 v111, v0
	v_mov_b32_e32 v120, v0
	v_mov_b32_e32 v121, v0
	v_mov_b32_e32 v122, v0
	v_mov_b32_e32 v123, v0
	v_mov_b32_e32 v124, v0
	v_mov_b32_e32 v125, v0
	v_mov_b32_e32 v126, v0
	v_mov_b32_e32 v127, v0
	v_mov_b32_e32 v136, v0
	v_mov_b32_e32 v137, v0
	v_mov_b32_e32 v138, v0
	v_mov_b32_e32 v139, v0
	v_mov_b32_e32 v140, v0
	v_mov_b32_e32 v141, v0
	v_mov_b32_e32 v142, v0
	v_mov_b32_e32 v143, v0
.LBB0_517:
	ds_read_b128 v[64:67], v175
	ds_read_b128 v[68:71], v175 offset:1024
	ds_read_b128 v[80:83], v175 offset:2048
	ds_read_b128 v[84:87], v175 offset:3072
	s_add_u32 s34, s30, 0xfffe0080
	s_addc_u32 s35, s31, -1
	s_cmp_eq_u32 s80, 0
	s_cselect_b32 s37, s1, s35
	s_cselect_b32 s36, s25, s34
	s_cselect_b32 s35, s23, s67
	s_cselect_b32 s34, s65, s66
	v_lshl_add_u64 v[204:205], s[30:31], 0, v[154:155]
	s_add_i32 m0, s46, 0xc000
	ds_read_b128 v[162:165], v176
	ds_read_b128 v[166:169], v176 offset:1024
	ds_read_b128 v[180:183], v176 offset:2048
	ds_read_b128 v[184:187], v176 offset:3072
	ds_read_b128 v[188:191], v176 offset:4096
	ds_read_b128 v[192:195], v176 offset:5120
	ds_read_b128 v[196:199], v176 offset:6144
	ds_read_b128 v[200:203], v176 offset:7168
	global_load_lds_dwordx4 v[204:205], off
	v_lshl_add_u64 v[204:205], s[30:31], 0, v[156:157]
	s_add_i32 m0, s46, 0xe000
	s_nop 0
	global_load_lds_dwordx4 v[204:205], off
	s_waitcnt lgkmcnt(8)
	s_barrier
	s_waitcnt lgkmcnt(0)
	s_setprio 1
	s_waitcnt lgkmcnt(0)
	v_mfma_f32_16x16x32_bf16 v[140:143], v[64:67], v[162:165], v[140:143]
	v_mfma_f32_16x16x32_bf16 v[136:139], v[80:83], v[162:165], v[136:139]
	v_mfma_f32_16x16x32_bf16 v[124:127], v[64:67], v[180:183], v[124:127]
	v_mfma_f32_16x16x32_bf16 v[120:123], v[80:83], v[180:183], v[120:123]
	v_mfma_f32_16x16x32_bf16 v[108:111], v[64:67], v[188:191], v[108:111]
	v_mfma_f32_16x16x32_bf16 v[104:107], v[80:83], v[188:191], v[104:107]
	v_mfma_f32_16x16x32_bf16 v[92:95], v[64:67], v[196:199], v[92:95]
	v_mfma_f32_16x16x32_bf16 v[88:91], v[80:83], v[196:199], v[88:91]
	v_mfma_f32_16x16x32_bf16 v[140:143], v[68:71], v[166:169], v[140:143]
	v_mfma_f32_16x16x32_bf16 v[136:139], v[84:87], v[166:169], v[136:139]
	v_mfma_f32_16x16x32_bf16 v[124:127], v[68:71], v[184:187], v[124:127]
	v_mfma_f32_16x16x32_bf16 v[120:123], v[84:87], v[184:187], v[120:123]
	v_mfma_f32_16x16x32_bf16 v[108:111], v[68:71], v[192:195], v[108:111]
	v_mfma_f32_16x16x32_bf16 v[104:107], v[84:87], v[192:195], v[104:107]
	v_mfma_f32_16x16x32_bf16 v[92:95], v[68:71], v[200:203], v[92:95]
	v_mfma_f32_16x16x32_bf16 v[88:91], v[84:87], v[200:203], v[88:91]
	s_setprio 0
	s_barrier
	s_add_i32 s81, s55, s43
	v_lshl_add_u64 v[220:221], s[34:35], 0, v[148:149]
	s_mov_b32 m0, s81
	ds_read_b128 v[204:207], v177
	ds_read_b128 v[208:211], v177 offset:1024
	ds_read_b128 v[212:215], v177 offset:2048
	ds_read_b128 v[216:219], v177 offset:3072
	global_load_lds_dwordx4 v[220:221], off
	v_lshl_add_u64 v[222:223], s[34:35], 0, v[144:145]
	s_add_i32 m0, s81, 0x2000
	s_nop 0
	global_load_lds_dwordx4 v[222:223], off
	s_barrier
	s_waitcnt lgkmcnt(0)
	s_setprio 1
	s_waitcnt lgkmcnt(0)
	v_mfma_f32_16x16x32_bf16 v[132:135], v[204:207], v[162:165], v[132:135]
	v_mfma_f32_16x16x32_bf16 v[128:131], v[212:215], v[162:165], v[128:131]
	v_mfma_f32_16x16x32_bf16 v[116:119], v[204:207], v[180:183], v[116:119]
	v_mfma_f32_16x16x32_bf16 v[112:115], v[212:215], v[180:183], v[112:115]
	v_mfma_f32_16x16x32_bf16 v[100:103], v[204:207], v[188:191], v[100:103]
	v_mfma_f32_16x16x32_bf16 v[96:99], v[212:215], v[188:191], v[96:99]
	v_mfma_f32_16x16x32_bf16 v[76:79], v[204:207], v[196:199], v[76:79]
	v_mfma_f32_16x16x32_bf16 v[72:75], v[212:215], v[196:199], v[72:75]
	v_mfma_f32_16x16x32_bf16 v[132:135], v[208:211], v[166:169], v[132:135]
	v_mfma_f32_16x16x32_bf16 v[128:131], v[216:219], v[166:169], v[128:131]
	v_mfma_f32_16x16x32_bf16 v[116:119], v[208:211], v[184:187], v[116:119]
	v_mfma_f32_16x16x32_bf16 v[112:115], v[216:219], v[184:187], v[112:115]
	v_mfma_f32_16x16x32_bf16 v[100:103], v[208:211], v[192:195], v[100:103]
	v_mfma_f32_16x16x32_bf16 v[96:99], v[216:219], v[192:195], v[96:99]
	v_mfma_f32_16x16x32_bf16 v[76:79], v[208:211], v[200:203], v[76:79]
	v_mfma_f32_16x16x32_bf16 v[72:75], v[216:219], v[200:203], v[72:75]
	s_setprio 0
	s_mov_b32 m0, s46
	v_lshl_add_u64 v[224:225], s[36:37], 0, v[150:151]
	s_barrier
	ds_read_b128 v[162:165], v176 offset:16384
	ds_read_b128 v[166:169], v176 offset:17408
	ds_read_b128 v[180:183], v176 offset:18432
	ds_read_b128 v[184:187], v176 offset:19456
	ds_read_b128 v[188:191], v176 offset:20480
	ds_read_b128 v[192:195], v176 offset:21504
	ds_read_b128 v[196:199], v176 offset:22528
	ds_read_b128 v[200:203], v176 offset:23552
	global_load_lds_dwordx4 v[224:225], off
	v_lshl_add_u64 v[226:227], s[36:37], 0, v[146:147]
	s_mov_b32 m0, s47
	s_nop 0
	global_load_lds_dwordx4 v[226:227], off
	s_barrier
	s_waitcnt lgkmcnt(0)
	s_setprio 1
	s_waitcnt lgkmcnt(0)
	v_mfma_f32_16x16x32_bf16 v[60:63], v[64:67], v[162:165], v[60:63]
	v_mfma_f32_16x16x32_bf16 v[56:59], v[80:83], v[162:165], v[56:59]
	v_mfma_f32_16x16x32_bf16 v[44:47], v[64:67], v[180:183], v[44:47]
	v_mfma_f32_16x16x32_bf16 v[40:43], v[80:83], v[180:183], v[40:43]
	v_mfma_f32_16x16x32_bf16 v[28:31], v[64:67], v[188:191], v[28:31]
	v_mfma_f32_16x16x32_bf16 v[24:27], v[80:83], v[188:191], v[24:27]
	v_mfma_f32_16x16x32_bf16 v[12:15], v[64:67], v[196:199], v[12:15]
	v_mfma_f32_16x16x32_bf16 v[8:11], v[80:83], v[196:199], v[8:11]
	v_mfma_f32_16x16x32_bf16 v[60:63], v[68:71], v[166:169], v[60:63]
	v_mfma_f32_16x16x32_bf16 v[56:59], v[84:87], v[166:169], v[56:59]
	v_mfma_f32_16x16x32_bf16 v[44:47], v[68:71], v[184:187], v[44:47]
	v_mfma_f32_16x16x32_bf16 v[40:43], v[84:87], v[184:187], v[40:43]
	v_mfma_f32_16x16x32_bf16 v[28:31], v[68:71], v[192:195], v[28:31]
	v_mfma_f32_16x16x32_bf16 v[24:27], v[84:87], v[192:195], v[24:27]
	v_mfma_f32_16x16x32_bf16 v[12:15], v[68:71], v[200:203], v[12:15]
	v_mfma_f32_16x16x32_bf16 v[8:11], v[84:87], v[200:203], v[8:11]
	s_setprio 0
	s_barrier
	s_add_u32 s82, s34, 0x20000
	s_addc_u32 s83, s35, 0
	s_add_i32 s81, s56, s43
	v_lshl_add_u64 v[64:65], s[82:83], 0, v[148:149]
	s_mov_b32 m0, s81
	s_nop 0
	global_load_lds_dwordx4 v[64:65], off
	v_lshl_add_u64 v[64:65], s[82:83], 0, v[144:145]
	s_add_i32 m0, s81, 0x2000
	s_nop 0
	global_load_lds_dwordx4 v[64:65], off
	s_waitcnt vmcnt(6)
	s_barrier
	s_setprio 1
	v_mfma_f32_16x16x32_bf16 v[52:55], v[204:207], v[162:165], v[52:55]
	v_mfma_f32_16x16x32_bf16 v[48:51], v[212:215], v[162:165], v[48:51]
	v_mfma_f32_16x16x32_bf16 v[36:39], v[204:207], v[180:183], v[36:39]
	v_mfma_f32_16x16x32_bf16 v[32:35], v[212:215], v[180:183], v[32:35]
	v_mfma_f32_16x16x32_bf16 v[20:23], v[204:207], v[188:191], v[20:23]
	v_mfma_f32_16x16x32_bf16 v[16:19], v[212:215], v[188:191], v[16:19]
	v_mfma_f32_16x16x32_bf16 v[4:7], v[204:207], v[196:199], v[4:7]
	v_mfma_f32_16x16x32_bf16 v[0:3], v[212:215], v[196:199], v[0:3]
	v_mfma_f32_16x16x32_bf16 v[52:55], v[208:211], v[166:169], v[52:55]
	v_mfma_f32_16x16x32_bf16 v[48:51], v[216:219], v[166:169], v[48:51]
	v_mfma_f32_16x16x32_bf16 v[36:39], v[208:211], v[184:187], v[36:39]
	v_mfma_f32_16x16x32_bf16 v[32:35], v[216:219], v[184:187], v[32:35]
	v_mfma_f32_16x16x32_bf16 v[20:23], v[208:211], v[192:195], v[20:23]
	v_mfma_f32_16x16x32_bf16 v[16:19], v[216:219], v[192:195], v[16:19]
	v_mfma_f32_16x16x32_bf16 v[4:7], v[208:211], v[200:203], v[4:7]
	v_mfma_f32_16x16x32_bf16 v[0:3], v[216:219], v[200:203], v[0:3]
	s_setprio 0
	s_add_i32 s81, 0, 0x18000
	v_add_u32_e32 v84, s81, v173
	s_barrier
	ds_read_b128 v[64:67], v84
	ds_read_b128 v[68:71], v84 offset:1024
	ds_read_b128 v[80:83], v84 offset:2048
	ds_read_b128 v[84:87], v84 offset:3072
	s_add_u32 s36, s36, 0x20000
	s_addc_u32 s37, s37, 0
	s_mov_b32 m0, s48
	v_lshl_add_u64 v[204:205], s[36:37], 0, v[150:151]
	ds_read_b128 v[162:165], v176 offset:32768
	ds_read_b128 v[166:169], v176 offset:33792
	ds_read_b128 v[180:183], v176 offset:34816
	ds_read_b128 v[184:187], v176 offset:35840
	ds_read_b128 v[188:191], v176 offset:36864
	ds_read_b128 v[192:195], v176 offset:37888
	ds_read_b128 v[196:199], v176 offset:38912
	ds_read_b128 v[200:203], v176 offset:39936
	global_load_lds_dwordx4 v[204:205], off
	v_lshl_add_u64 v[204:205], s[36:37], 0, v[146:147]
	s_mov_b32 m0, s49
	s_nop 0
	global_load_lds_dwordx4 v[204:205], off
	s_waitcnt lgkmcnt(8)
	s_barrier
	s_waitcnt lgkmcnt(0)
	s_setprio 1
	s_waitcnt lgkmcnt(0)
	v_mfma_f32_16x16x32_bf16 v[140:143], v[64:67], v[162:165], v[140:143]
	v_mfma_f32_16x16x32_bf16 v[136:139], v[80:83], v[162:165], v[136:139]
	v_mfma_f32_16x16x32_bf16 v[124:127], v[64:67], v[180:183], v[124:127]
	v_mfma_f32_16x16x32_bf16 v[120:123], v[80:83], v[180:183], v[120:123]
	v_mfma_f32_16x16x32_bf16 v[108:111], v[64:67], v[188:191], v[108:111]
	v_mfma_f32_16x16x32_bf16 v[104:107], v[80:83], v[188:191], v[104:107]
	v_mfma_f32_16x16x32_bf16 v[92:95], v[64:67], v[196:199], v[92:95]
	v_mfma_f32_16x16x32_bf16 v[88:91], v[80:83], v[196:199], v[88:91]
	v_mfma_f32_16x16x32_bf16 v[140:143], v[68:71], v[166:169], v[140:143]
	v_mfma_f32_16x16x32_bf16 v[136:139], v[84:87], v[166:169], v[136:139]
	v_mfma_f32_16x16x32_bf16 v[124:127], v[68:71], v[184:187], v[124:127]
	v_mfma_f32_16x16x32_bf16 v[120:123], v[84:87], v[184:187], v[120:123]
	v_mfma_f32_16x16x32_bf16 v[108:111], v[68:71], v[192:195], v[108:111]
	v_mfma_f32_16x16x32_bf16 v[104:107], v[84:87], v[192:195], v[104:107]
	v_mfma_f32_16x16x32_bf16 v[92:95], v[68:71], v[200:203], v[92:95]
	v_mfma_f32_16x16x32_bf16 v[88:91], v[84:87], v[200:203], v[88:91]
	s_setprio 0
	s_barrier
	s_add_i32 s36, 0, 0x1c000
	s_add_i32 s37, s81, s43
	v_add_u32_e32 v152, s36, v173
	v_lshl_add_u64 v[220:221], v[220:221], 0, s[12:13]
	s_mov_b32 m0, s37
	ds_read_b128 v[204:207], v152
	ds_read_b128 v[208:211], v152 offset:1024
	ds_read_b128 v[212:215], v152 offset:2048
	ds_read_b128 v[216:219], v152 offset:3072
	global_load_lds_dwordx4 v[220:221], off
	v_lshl_add_u64 v[220:221], v[222:223], 0, s[12:13]
	s_add_i32 m0, s37, 0x2000
	s_nop 0
	global_load_lds_dwordx4 v[220:221], off
	s_barrier
	s_waitcnt lgkmcnt(0)
	s_setprio 1
	s_waitcnt lgkmcnt(0)
	v_mfma_f32_16x16x32_bf16 v[132:135], v[204:207], v[162:165], v[132:135]
	v_mfma_f32_16x16x32_bf16 v[128:131], v[212:215], v[162:165], v[128:131]
	v_mfma_f32_16x16x32_bf16 v[116:119], v[204:207], v[180:183], v[116:119]
	v_mfma_f32_16x16x32_bf16 v[112:115], v[212:215], v[180:183], v[112:115]
	v_mfma_f32_16x16x32_bf16 v[100:103], v[204:207], v[188:191], v[100:103]
	v_mfma_f32_16x16x32_bf16 v[96:99], v[212:215], v[188:191], v[96:99]
	v_mfma_f32_16x16x32_bf16 v[76:79], v[204:207], v[196:199], v[76:79]
	v_mfma_f32_16x16x32_bf16 v[72:75], v[212:215], v[196:199], v[72:75]
	v_mfma_f32_16x16x32_bf16 v[132:135], v[208:211], v[166:169], v[132:135]
	v_mfma_f32_16x16x32_bf16 v[128:131], v[216:219], v[166:169], v[128:131]
	v_mfma_f32_16x16x32_bf16 v[116:119], v[208:211], v[184:187], v[116:119]
	v_mfma_f32_16x16x32_bf16 v[112:115], v[216:219], v[184:187], v[112:115]
	v_mfma_f32_16x16x32_bf16 v[100:103], v[208:211], v[192:195], v[100:103]
	v_mfma_f32_16x16x32_bf16 v[96:99], v[216:219], v[192:195], v[96:99]
	v_mfma_f32_16x16x32_bf16 v[76:79], v[208:211], v[200:203], v[76:79]
	v_mfma_f32_16x16x32_bf16 v[72:75], v[216:219], v[200:203], v[72:75]
	s_setprio 0
	s_mov_b32 m0, s51
	v_lshl_add_u64 v[220:221], v[224:225], 0, s[12:13]
	s_barrier
	ds_read_b128 v[162:165], v176 offset:49152
	ds_read_b128 v[166:169], v176 offset:50176
	ds_read_b128 v[180:183], v176 offset:51200
	ds_read_b128 v[184:187], v176 offset:52224
	ds_read_b128 v[188:191], v176 offset:53248
	ds_read_b128 v[192:195], v176 offset:54272
	ds_read_b128 v[196:199], v176 offset:55296
	ds_read_b128 v[200:203], v176 offset:56320
	global_load_lds_dwordx4 v[220:221], off
	v_lshl_add_u64 v[220:221], v[226:227], 0, s[12:13]
	s_mov_b32 m0, s52
	s_nop 0
	global_load_lds_dwordx4 v[220:221], off
	s_barrier
	s_waitcnt lgkmcnt(0)
	s_setprio 1
	s_waitcnt lgkmcnt(0)
	v_mfma_f32_16x16x32_bf16 v[60:63], v[64:67], v[162:165], v[60:63]
	v_mfma_f32_16x16x32_bf16 v[56:59], v[80:83], v[162:165], v[56:59]
	v_mfma_f32_16x16x32_bf16 v[44:47], v[64:67], v[180:183], v[44:47]
	v_mfma_f32_16x16x32_bf16 v[40:43], v[80:83], v[180:183], v[40:43]
	v_mfma_f32_16x16x32_bf16 v[28:31], v[64:67], v[188:191], v[28:31]
	v_mfma_f32_16x16x32_bf16 v[24:27], v[80:83], v[188:191], v[24:27]
	v_mfma_f32_16x16x32_bf16 v[12:15], v[64:67], v[196:199], v[12:15]
	v_mfma_f32_16x16x32_bf16 v[8:11], v[80:83], v[196:199], v[8:11]
	v_mfma_f32_16x16x32_bf16 v[60:63], v[68:71], v[166:169], v[60:63]
	v_mfma_f32_16x16x32_bf16 v[56:59], v[84:87], v[166:169], v[56:59]
	v_mfma_f32_16x16x32_bf16 v[44:47], v[68:71], v[184:187], v[44:47]
	v_mfma_f32_16x16x32_bf16 v[40:43], v[84:87], v[184:187], v[40:43]
	v_mfma_f32_16x16x32_bf16 v[28:31], v[68:71], v[192:195], v[28:31]
	v_mfma_f32_16x16x32_bf16 v[24:27], v[84:87], v[192:195], v[24:27]
	v_mfma_f32_16x16x32_bf16 v[12:15], v[68:71], v[200:203], v[12:15]
	v_mfma_f32_16x16x32_bf16 v[8:11], v[84:87], v[200:203], v[8:11]
	s_setprio 0
	s_barrier
	s_add_u32 s34, s34, 0x20080
	s_addc_u32 s35, s35, 0
	s_add_i32 s36, s36, s43
	v_lshl_add_u64 v[64:65], s[34:35], 0, v[148:149]
	s_mov_b32 m0, s36
	s_nop 0
	global_load_lds_dwordx4 v[64:65], off
	v_lshl_add_u64 v[64:65], s[34:35], 0, v[144:145]
	s_add_i32 m0, s36, 0x2000
	s_nop 0
	global_load_lds_dwordx4 v[64:65], off
	s_waitcnt vmcnt(6)
	s_barrier
	s_setprio 1
	v_mfma_f32_16x16x32_bf16 v[52:55], v[204:207], v[162:165], v[52:55]
	v_mfma_f32_16x16x32_bf16 v[48:51], v[212:215], v[162:165], v[48:51]
	v_mfma_f32_16x16x32_bf16 v[36:39], v[204:207], v[180:183], v[36:39]
	v_mfma_f32_16x16x32_bf16 v[32:35], v[212:215], v[180:183], v[32:35]
	v_mfma_f32_16x16x32_bf16 v[20:23], v[204:207], v[188:191], v[20:23]
	v_mfma_f32_16x16x32_bf16 v[16:19], v[212:215], v[188:191], v[16:19]
	v_mfma_f32_16x16x32_bf16 v[4:7], v[204:207], v[196:199], v[4:7]
	v_mfma_f32_16x16x32_bf16 v[0:3], v[212:215], v[196:199], v[0:3]
	v_mfma_f32_16x16x32_bf16 v[52:55], v[208:211], v[166:169], v[52:55]
	v_mfma_f32_16x16x32_bf16 v[48:51], v[216:219], v[166:169], v[48:51]
	v_mfma_f32_16x16x32_bf16 v[36:39], v[208:211], v[184:187], v[36:39]
	v_mfma_f32_16x16x32_bf16 v[32:35], v[216:219], v[184:187], v[32:35]
	v_mfma_f32_16x16x32_bf16 v[20:23], v[208:211], v[192:195], v[20:23]
	v_mfma_f32_16x16x32_bf16 v[16:19], v[216:219], v[192:195], v[16:19]
	v_mfma_f32_16x16x32_bf16 v[4:7], v[208:211], v[200:203], v[4:7]
	v_mfma_f32_16x16x32_bf16 v[0:3], v[216:219], v[200:203], v[0:3]
	s_setprio 0
	s_add_i32 s80, s80, 2
	s_add_u32 s30, s30, 0x100
	s_addc_u32 s31, s31, 0
	s_add_u32 s66, s66, 0x100
	s_addc_u32 s67, s67, 0
	s_cmp_gt_u32 s80, 1
	s_barrier
	s_cbranch_scc0 .LBB0_517
	v_lshl_add_u32 v164, s0, 8, v172
	s_lshl_b32 s0, s33, 8
	s_and_b32 s0, s0, 0x300
	v_or_b32_e32 v179, s0, v174
	s_cmp_gt_u32 s33, 3
	s_mov_b64 s[0:1], -1
	s_cbranch_scc0 .LBB0_524
	s_cmp_gt_u32 s33, 7
	s_cbranch_scc0 .LBB0_521
	v_lshlrev_b32_e32 v152, 1, v179
	v_ashrrev_i32_e32 v165, 31, v164
	v_lshl_add_u64 v[70:71], s[10:11], 0, v[152:153]
	v_lshlrev_b64 v[64:65], 11, v[164:165]
	v_pk_add_f32 v[68:69], v[142:143], 0 op_sel_hi:[1,0]
	v_pk_add_f32 v[66:67], v[140:141], 0 op_sel_hi:[1,0]
	v_pk_add_f32 v[80:81], v[138:139], 0 op_sel_hi:[1,0]
	v_pk_add_f32 v[82:83], v[136:137], 0 op_sel_hi:[1,0]
	v_lshl_add_u64 v[64:65], v[70:71], 0, v[64:65]
	v_cvt_pk_bf16_f32 v66, v66, v67
	v_cvt_pk_bf16_f32 v67, v68, v69
	v_cvt_pk_bf16_f32 v68, v82, v83
	v_cvt_pk_bf16_f32 v69, v80, v81
	global_store_dwordx4 v[64:65], v[66:69], off
	v_pk_add_f32 v[80:81], v[130:131], 0 op_sel_hi:[1,0]
	v_pk_add_f32 v[82:83], v[128:129], 0 op_sel_hi:[1,0]
	v_pk_add_f32 v[68:69], v[134:135], 0 op_sel_hi:[1,0]
	v_pk_add_f32 v[66:67], v[132:133], 0 op_sel_hi:[1,0]
	v_pk_add_f32 v[84:85], v[120:121], 0 op_sel_hi:[1,0]
	v_cvt_pk_bf16_f32 v66, v66, v67
	v_cvt_pk_bf16_f32 v67, v68, v69
	v_cvt_pk_bf16_f32 v68, v82, v83
	v_cvt_pk_bf16_f32 v69, v80, v81
	global_store_dwordx4 v[64:65], v[66:69], off offset:256
	v_pk_add_f32 v[82:83], v[122:123], 0 op_sel_hi:[1,0]
	v_lshl_add_u64 v[166:167], v[64:65], 0, s[20:21]
	v_or_b32_e32 v66, 16, v164
	v_ashrrev_i32_e32 v67, 31, v66
	v_lshlrev_b64 v[66:67], 11, v[66:67]
	v_lshl_add_u64 v[80:81], v[70:71], 0, v[66:67]
	v_pk_add_f32 v[68:69], v[126:127], 0 op_sel_hi:[1,0]
	v_pk_add_f32 v[66:67], v[124:125], 0 op_sel_hi:[1,0]
	s_mov_b64 s[0:1], 0
	v_cvt_pk_bf16_f32 v66, v66, v67
	v_cvt_pk_bf16_f32 v67, v68, v69
	v_cvt_pk_bf16_f32 v68, v84, v85
	v_cvt_pk_bf16_f32 v69, v82, v83
	global_store_dwordx4 v[80:81], v[66:69], off
	v_pk_add_f32 v[82:83], v[114:115], 0 op_sel_hi:[1,0]
	v_pk_add_f32 v[84:85], v[112:113], 0 op_sel_hi:[1,0]
	v_pk_add_f32 v[68:69], v[118:119], 0 op_sel_hi:[1,0]
	v_pk_add_f32 v[66:67], v[116:117], 0 op_sel_hi:[1,0]
	s_nop 0
	v_cvt_pk_bf16_f32 v66, v66, v67
	v_cvt_pk_bf16_f32 v67, v68, v69
	v_cvt_pk_bf16_f32 v68, v84, v85
	v_cvt_pk_bf16_f32 v69, v82, v83
	global_store_dwordx4 v[80:81], v[66:69], off offset:256
	v_pk_add_f32 v[82:83], v[106:107], 0 op_sel_hi:[1,0]
	v_pk_add_f32 v[84:85], v[104:105], 0 op_sel_hi:[1,0]
	v_or_b32_e32 v66, 32, v164
	v_ashrrev_i32_e32 v67, 31, v66
	v_lshlrev_b64 v[66:67], 11, v[66:67]
	v_lshl_add_u64 v[80:81], v[70:71], 0, v[66:67]
	v_pk_add_f32 v[68:69], v[110:111], 0 op_sel_hi:[1,0]
	v_pk_add_f32 v[66:67], v[108:109], 0 op_sel_hi:[1,0]
	s_nop 0
	v_cvt_pk_bf16_f32 v66, v66, v67
	v_cvt_pk_bf16_f32 v67, v68, v69
	v_cvt_pk_bf16_f32 v68, v84, v85
	v_cvt_pk_bf16_f32 v69, v82, v83
	global_store_dwordx4 v[80:81], v[66:69], off
	v_pk_add_f32 v[82:83], v[98:99], 0 op_sel_hi:[1,0]
	v_pk_add_f32 v[84:85], v[96:97], 0 op_sel_hi:[1,0]
	v_pk_add_f32 v[68:69], v[102:103], 0 op_sel_hi:[1,0]
	v_pk_add_f32 v[66:67], v[100:101], 0 op_sel_hi:[1,0]
	s_nop 0
	v_cvt_pk_bf16_f32 v66, v66, v67
	v_cvt_pk_bf16_f32 v67, v68, v69
	v_cvt_pk_bf16_f32 v68, v84, v85
	v_cvt_pk_bf16_f32 v69, v82, v83
	global_store_dwordx4 v[80:81], v[66:69], off offset:256
	v_pk_add_f32 v[80:81], v[90:91], 0 op_sel_hi:[1,0]
	v_pk_add_f32 v[82:83], v[88:89], 0 op_sel_hi:[1,0]
	v_or_b32_e32 v66, 48, v164
	v_ashrrev_i32_e32 v67, 31, v66
	v_lshlrev_b64 v[66:67], 11, v[66:67]
	v_lshl_add_u64 v[70:71], v[70:71], 0, v[66:67]
	v_pk_add_f32 v[68:69], v[94:95], 0 op_sel_hi:[1,0]
	v_pk_add_f32 v[66:67], v[92:93], 0 op_sel_hi:[1,0]
	s_nop 0
	v_cvt_pk_bf16_f32 v66, v66, v67
	v_cvt_pk_bf16_f32 v67, v68, v69
	v_cvt_pk_bf16_f32 v68, v82, v83
	v_cvt_pk_bf16_f32 v69, v80, v81
	global_store_dwordx4 v[70:71], v[66:69], off
	v_pk_add_f32 v[80:81], v[74:75], 0 op_sel_hi:[1,0]
	v_pk_add_f32 v[82:83], v[72:73], 0 op_sel_hi:[1,0]
	v_pk_add_f32 v[68:69], v[78:79], 0 op_sel_hi:[1,0]
	v_pk_add_f32 v[66:67], v[76:77], 0 op_sel_hi:[1,0]
	s_nop 0
	v_cvt_pk_bf16_f32 v66, v66, v67
	v_cvt_pk_bf16_f32 v67, v68, v69
	v_cvt_pk_bf16_f32 v68, v82, v83
	v_cvt_pk_bf16_f32 v69, v80, v81
	global_store_dwordx4 v[70:71], v[66:69], off offset:256
	v_pk_add_f32 v[80:81], v[58:59], 0 op_sel_hi:[1,0]
	v_pk_add_f32 v[82:83], v[56:57], 0 op_sel_hi:[1,0]
	v_pk_add_f32 v[68:69], v[62:63], 0 op_sel_hi:[1,0]
	v_pk_add_f32 v[66:67], v[60:61], 0 op_sel_hi:[1,0]
	v_lshl_add_u64 v[70:71], v[64:65], 0, s[14:15]
	v_cvt_pk_bf16_f32 v66, v66, v67
	v_cvt_pk_bf16_f32 v67, v68, v69
	v_cvt_pk_bf16_f32 v69, v80, v81
	v_add_co_u32_e32 v80, vcc, s57, v64
	v_cvt_pk_bf16_f32 v68, v82, v83
	s_nop 0
	v_addc_co_u32_e32 v81, vcc, 0, v65, vcc
	global_store_dwordx4 v[80:81], v[66:69], off
	v_pk_add_f32 v[80:81], v[50:51], 0 op_sel_hi:[1,0]
	v_pk_add_f32 v[82:83], v[48:49], 0 op_sel_hi:[1,0]
	v_pk_add_f32 v[68:69], v[54:55], 0 op_sel_hi:[1,0]
	v_pk_add_f32 v[66:67], v[52:53], 0 op_sel_hi:[1,0]
	s_nop 0
	v_cvt_pk_bf16_f32 v66, v66, v67
	v_cvt_pk_bf16_f32 v67, v68, v69
	v_cvt_pk_bf16_f32 v68, v82, v83
	v_cvt_pk_bf16_f32 v69, v80, v81
	global_store_dwordx4 v[70:71], v[66:69], off offset:256
	v_pk_add_f32 v[80:81], v[42:43], 0 op_sel_hi:[1,0]
	v_pk_add_f32 v[82:83], v[40:41], 0 op_sel_hi:[1,0]
	v_pk_add_f32 v[68:69], v[46:47], 0 op_sel_hi:[1,0]
	v_pk_add_f32 v[66:67], v[44:45], 0 op_sel_hi:[1,0]
	v_lshl_add_u64 v[70:71], v[64:65], 0, s[16:17]
	v_cvt_pk_bf16_f32 v66, v66, v67
	v_cvt_pk_bf16_f32 v67, v68, v69
	v_cvt_pk_bf16_f32 v69, v80, v81
	v_add_co_u32_e32 v80, vcc, s58, v64
	v_cvt_pk_bf16_f32 v68, v82, v83
	s_nop 0
	v_addc_co_u32_e32 v81, vcc, 0, v65, vcc
	global_store_dwordx4 v[80:81], v[66:69], off
	v_pk_add_f32 v[80:81], v[34:35], 0 op_sel_hi:[1,0]
	v_pk_add_f32 v[82:83], v[32:33], 0 op_sel_hi:[1,0]
	v_pk_add_f32 v[68:69], v[38:39], 0 op_sel_hi:[1,0]
	v_pk_add_f32 v[66:67], v[36:37], 0 op_sel_hi:[1,0]
	s_nop 0
	v_cvt_pk_bf16_f32 v66, v66, v67
	v_cvt_pk_bf16_f32 v67, v68, v69
	v_cvt_pk_bf16_f32 v68, v82, v83
	v_cvt_pk_bf16_f32 v69, v80, v81
	global_store_dwordx4 v[70:71], v[66:69], off offset:256
	v_pk_add_f32 v[80:81], v[26:27], 0 op_sel_hi:[1,0]
	v_pk_add_f32 v[82:83], v[24:25], 0 op_sel_hi:[1,0]
	v_pk_add_f32 v[68:69], v[30:31], 0 op_sel_hi:[1,0]
	v_pk_add_f32 v[66:67], v[28:29], 0 op_sel_hi:[1,0]
	v_lshl_add_u64 v[70:71], v[64:65], 0, s[18:19]
	v_cvt_pk_bf16_f32 v66, v66, v67
	v_cvt_pk_bf16_f32 v67, v68, v69
	v_cvt_pk_bf16_f32 v69, v80, v81
	v_add_co_u32_e32 v80, vcc, s59, v64
	v_cvt_pk_bf16_f32 v68, v82, v83
	s_nop 0
	v_addc_co_u32_e32 v81, vcc, 0, v65, vcc
	global_store_dwordx4 v[80:81], v[66:69], off
	v_pk_add_f32 v[80:81], v[18:19], 0 op_sel_hi:[1,0]
	v_pk_add_f32 v[82:83], v[16:17], 0 op_sel_hi:[1,0]
	v_pk_add_f32 v[68:69], v[22:23], 0 op_sel_hi:[1,0]
	v_pk_add_f32 v[66:67], v[20:21], 0 op_sel_hi:[1,0]
	v_add_co_u32_e32 v64, vcc, s60, v64
	v_cvt_pk_bf16_f32 v66, v66, v67
	v_cvt_pk_bf16_f32 v67, v68, v69
	v_cvt_pk_bf16_f32 v68, v82, v83
	v_cvt_pk_bf16_f32 v69, v80, v81
	global_store_dwordx4 v[70:71], v[66:69], off offset:256
	v_pk_add_f32 v[70:71], v[10:11], 0 op_sel_hi:[1,0]
	v_pk_add_f32 v[80:81], v[8:9], 0 op_sel_hi:[1,0]
	v_pk_add_f32 v[68:69], v[14:15], 0 op_sel_hi:[1,0]
	v_pk_add_f32 v[66:67], v[12:13], 0 op_sel_hi:[1,0]
	v_addc_co_u32_e32 v65, vcc, 0, v65, vcc
	v_cvt_pk_bf16_f32 v66, v66, v67
	v_cvt_pk_bf16_f32 v67, v68, v69
	v_cvt_pk_bf16_f32 v68, v80, v81
	v_cvt_pk_bf16_f32 v69, v70, v71
	global_store_dwordx4 v[64:65], v[66:69], off
	v_pk_add_f32 v[64:65], v[4:5], 0 op_sel_hi:[1,0]
	v_pk_add_f32 v[70:71], v[0:1], 0 op_sel_hi:[1,0]
	v_pk_add_f32 v[66:67], v[6:7], 0 op_sel_hi:[1,0]
	v_pk_add_f32 v[68:69], v[2:3], 0 op_sel_hi:[1,0]
	v_cvt_pk_bf16_f32 v64, v64, v65
	v_cvt_pk_bf16_f32 v65, v66, v67
	v_cvt_pk_bf16_f32 v66, v70, v71
